# attention: 10-quad fragment ring (one ds_read per MFMA, lookahead 10); hyena pointwise_data Hs loads prefetched one iteration ahead
# speedup vs baseline: 1.0303x; 1.0082x over previous
; #define LAS __attribute__((address_space(3)))
; __device__ __forceinline__ void pointwise_data(LAS f32x2* X, const f32x4* Hs, int tid) {
; #pragma unroll 4
;     for (int s = tid; s < 8192; s += NTHR) {
;         const f32x4 hh = Hs[s];
.LBB0_108:
	s_or_b64 exec, exec, s[66:67]
	v_readlane_b32 s0, v255, 29
	v_readlane_b32 s1, v255, 30
	s_and_b64 exec, exec, s[0:1]
	s_cbranch_execz .LBB0_127
	v_readlane_b32 s0, v255, 4
	v_ashrrev_i32_e32 v5, 31, v4
	v_readlane_b32 s1, v255, 5
	v_lshl_add_u32 v8, v4, 4, 0
	v_lshl_add_u32 v9, v4, 1, v200
	v_lshl_add_u64 v[6:7], v[4:5], 4, s[0:1]
	s_mov_b64 s[66:67], 0
	v_add_co_u32_e32 v244, vcc, 0xffffa000, v6
	s_nop 1
	v_addc_co_u32_e32 v245, vcc, -1, v7, vcc
	global_load_dwordx4 v[228:231], v[244:245], off
	v_add_co_u32_e32 v244, vcc, 0xffffc000, v6
	s_nop 1
	v_addc_co_u32_e32 v245, vcc, -1, v7, vcc
	global_load_dwordx4 v[232:235], v[244:245], off
	v_add_co_u32_e32 v244, vcc, 0xffffe000, v6
	s_nop 1
	v_addc_co_u32_e32 v245, vcc, -1, v7, vcc
	global_load_dwordx4 v[236:239], v[244:245], off
	global_load_dwordx4 v[240:243], v[6:7], off
	s_branch .LBB0_111

; __device__ __forceinline__ void pointwise_data(LAS f32x2* X, const f32x4* Hs, int tid) {
;     ...
;     for (int s = tid; s < 8192; s += NTHR) {
;         const f32x4 hh = Hs[s];
;         if (s == 0) {
;             const f32x2 A = X[0]; const float Y0 = (A.x + A.y) * hh.x, YM = (A.x - A.y) * hh.y; X[0] = (f32x2){0.5f * (Y0 + YM), 0.5f * (Y0 - YM)};
;             const f32x2 Cm = X[1]; const f32x2 Y = cmul((f32x2){Cm.x, -Cm.y}, (f32x2){hh.z, hh.w}); X[1] = (f32x2){Y.x, -Y.y};
;         } else {
;             const int i1 = 2 * s, i2 = i1 ^ ((1 << (31 - __clz(i1))) - 1); const int p = (int)(__brev((unsigned)i1) >> 18);
;             const f32x2 A = X[i1], B = X[i2];
;             const f32x2 E = {0.5f * (A.x + B.x), 0.5f * (A.y - B.y)}; const f32x2 Dm = {A.x - B.x, A.y + B.y}; const f32x2 O = {0.5f * Dm.y, -0.5f * Dm.x};
;             const float rev = (float)p * (1.f / 32768.f); const float c = __builtin_amdgcn_cosf(rev), sn = __builtin_amdgcn_sinf(rev);
;             const f32x2 WO = cmul((f32x2){c, -sn}, O);
;             const f32x2 Xk = E + WO; const f32x2 Xk2 = {E.x - WO.x, -(E.y - WO.y)};
;             const f32x2 Yk = cmul(Xk, (f32x2){hh.x, hh.y}), Yk2 = cmul(Xk2, (f32x2){hh.z, hh.w});
;             const f32x2 Ye = {0.5f * (Yk.x + Yk2.x), 0.5f * (Yk.y - Yk2.y)}; const f32x2 Dd = {Yk.x - Yk2.x, Yk.y + Yk2.y};
;             const f32x2 Yo = cmul((f32x2){0.5f * c, 0.5f * sn}, Dd);
;             X[i1] = (f32x2){Ye.x - Yo.y, Ye.y + Yo.x}; X[i2] = (f32x2){Ye.x + Yo.y, Yo.x - Ye.y};
.LBB0_111:
	s_nop 1
	s_waitcnt vmcnt(3)
	v_mov_b32_e32 v0, v228
	v_mov_b32_e32 v1, v229
	v_mov_b32_e32 v2, v230
	v_mov_b32_e32 v3, v231
	v_add_co_u32_e32 v244, vcc, 0x2000, v6
	s_nop 1
	v_addc_co_u32_e32 v245, vcc, 0, v7, vcc
	global_load_dwordx4 v[228:231], v[244:245], off
	v_cmp_ne_u32_e32 vcc, 0, v4
	s_and_saveexec_b64 s[0:1], vcc
	s_xor_b64 s[74:75], exec, s[0:1]
	s_cbranch_execz .LBB0_113
	v_add_u32_e32 v5, 0xfffff400, v9
	v_ffbh_u32_e32 v10, v5
	v_lshrrev_b32_e64 v10, v10, s62
	v_add_u32_e32 v10, -1, v10
	v_xor_b32_e32 v22, v10, v5
	v_bfrev_b32_e32 v5, v5
	v_lshrrev_b32_e32 v5, 18, v5
	v_lshl_add_u32 v51, v22, 3, 0
	v_cvt_f32_u32_e32 v5, v5
	ds_read_b64 v[10:11], v8
	ds_read_b64 v[22:23], v51
	v_mul_f32_e32 v5, 0x38000000, v5
	v_cos_f32_e32 v162, v5
	s_waitcnt lgkmcnt(0)
	v_pk_add_f32 v[38:39], v[10:11], v[22:23] neg_lo:[0,1] neg_hi:[0,1]
	v_pk_add_f32 v[10:11], v[10:11], v[22:23]
	v_sin_f32_e32 v22, v5
	v_mul_f32_e32 v166, -0.5, v38
	v_mov_b32_e32 v23, v162
	v_mul_f32_e32 v164, 0.5, v11
	v_xor_b32_e32 v163, 0x80000000, v22
	v_pk_mul_f32 v[166:167], v[22:23], v[166:167] op_sel_hi:[1,0]
	v_pk_mov_b32 v[10:11], v[38:39], v[10:11] op_sel:[1,0]
	v_pk_fma_f32 v[164:165], v[162:163], v[164:165], v[166:167] op_sel_hi:[1,0,1]
	v_pk_mul_f32 v[38:39], v[10:11], 0.5 op_sel_hi:[1,0]
	v_pk_fma_f32 v[10:11], v[10:11], 0.5, v[164:165] op_sel:[0,0,1] op_sel_hi:[1,0,0] neg_lo:[0,0,1] neg_hi:[0,0,1]
	v_pk_add_f32 v[38:39], v[38:39], v[164:165] op_sel:[1,0] op_sel_hi:[0,1]
	v_xor_b32_e32 v166, 0x80000000, v39
	v_mov_b32_e32 v167, v38
	v_pk_mul_f32 v[166:167], v[0:1], v[166:167] op_sel:[1,0]
	v_xor_b32_e32 v165, 0x80000000, v10
	v_pk_fma_f32 v[0:1], v[0:1], v[38:39], v[166:167] op_sel_hi:[0,1,1]
	v_mov_b32_e32 v38, v3
	v_mov_b32_e32 v164, v11
	v_pk_mul_f32 v[10:11], v[38:39], v[10:11] op_sel_hi:[0,1]
	v_pk_fma_f32 v[2:3], v[2:3], v[164:165], v[10:11] op_sel_hi:[0,1,1]
	v_mov_b32_e32 v163, v22
	v_pk_add_f32 v[10:11], v[0:1], v[2:3] neg_lo:[0,1] neg_hi:[0,1]
	v_pk_add_f32 v[0:1], v[0:1], v[2:3]
	v_pk_mul_f32 v[2:3], v[162:163], 0.5 op_sel_hi:[1,0]
	s_nop 0
	v_xor_b32_e32 v22, 0x80000000, v3
	v_mov_b32_e32 v23, v2
	v_pk_mul_f32 v[22:23], v[22:23], v[0:1] op_sel:[0,1]
	s_nop 0
	v_pk_fma_f32 v[2:3], v[2:3], v[10:11], v[22:23] op_sel_hi:[1,0,1]
	v_mov_b32_e32 v10, v0
	v_pk_fma_f32 v[0:1], v[0:1], 0.5, v[2:3] op_sel:[0,0,1] op_sel_hi:[1,0,0] neg_lo:[0,0,1] neg_hi:[0,0,1]
	v_pk_fma_f32 v[22:23], v[10:11], 0.5, v[2:3] op_sel:[0,0,1] op_sel_hi:[1,0,0]
	s_nop 0
	v_mov_b32_e32 v1, v23
	ds_write_b64 v8, v[0:1]
	v_pk_fma_f32 v[0:1], v[10:11], 0.5, v[2:3] op_sel_hi:[1,0,0] neg_lo:[1,0,0] neg_hi:[1,0,0]
	s_nop 0
	v_mov_b32_e32 v23, v1
	ds_write_b64 v51, v[22:23]
.LBB0_113:
	s_andn2_saveexec_b64 s[74:75], s[74:75]
	s_cbranch_execz .LBB0_115
	ds_read_b128 v[162:165], v173
	s_waitcnt lgkmcnt(0)
	v_add_f32_e32 v5, v162, v163
	v_sub_f32_e32 v10, v162, v163
	v_mul_f32_e32 v22, v0, v5
	v_mul_f32_e32 v1, v1, v10
	v_add_f32_e32 v22, v22, v1
	v_fma_f32 v23, v0, v5, -v1
	v_pk_mul_f32 v[0:1], v[22:23], 0.5 op_sel_hi:[1,0]
	v_mov_b32_e32 v22, v3
	v_xor_b32_e32 v11, 0x80000000, v165
	v_mov_b32_e32 v10, v164
	v_pk_mul_f32 v[22:23], v[22:23], v[164:165] op_sel:[0,1] op_sel_hi:[0,0]
	v_pk_fma_f32 v[2:3], v[2:3], v[10:11], v[22:23] op_sel_hi:[0,1,1]
	v_xor_b32_e32 v3, 0x80000000, v3
	ds_write_b128 v173, v[0:3]
.LBB0_115:
	s_or_b64 exec, exec, s[74:75]
	v_add_u32_e32 v5, 0x200, v4
	s_nop 0
	s_waitcnt vmcnt(3)
	v_mov_b32_e32 v0, v232
	v_mov_b32_e32 v1, v233
	v_mov_b32_e32 v2, v234
	v_mov_b32_e32 v3, v235
	v_add_co_u32_e32 v244, vcc, 0x4000, v6
	s_nop 1
	v_addc_co_u32_e32 v245, vcc, 0, v7, vcc
	global_load_dwordx4 v[232:235], v[244:245], off
	v_cmp_ne_u32_e32 vcc, 0, v5
	s_and_saveexec_b64 s[0:1], vcc
	s_xor_b64 s[74:75], exec, s[0:1]
	s_cbranch_execz .LBB0_117
	v_add_u32_e32 v38, 0xfffff800, v9
	v_ffbh_u32_e32 v10, v38
	v_lshrrev_b32_e64 v10, v10, s62
	v_add_u32_e32 v10, -1, v10
	v_xor_b32_e32 v22, v10, v38
	v_lshl_add_u32 v51, v22, 3, 0
	v_bfrev_b32_e32 v38, v38
	ds_read_b64 v[10:11], v8 offset:8192
	ds_read_b64 v[22:23], v51
	v_lshrrev_b32_e32 v38, 18, v38
	v_cvt_f32_u32_e32 v53, v38
	s_waitcnt lgkmcnt(0)
	v_pk_add_f32 v[38:39], v[10:11], v[22:23] neg_lo:[0,1] neg_hi:[0,1]
	v_pk_add_f32 v[10:11], v[10:11], v[22:23]
	v_mul_f32_e32 v23, 0x38000000, v53
	v_cos_f32_e32 v162, v23
	v_sin_f32_e32 v22, v23
	v_mul_f32_e32 v166, -0.5, v38
	v_mul_f32_e32 v164, 0.5, v11
	v_mov_b32_e32 v23, v162
	v_xor_b32_e32 v163, 0x80000000, v22
	v_pk_mul_f32 v[166:167], v[22:23], v[166:167] op_sel_hi:[1,0]
	v_pk_mov_b32 v[10:11], v[38:39], v[10:11] op_sel:[1,0]
	v_pk_fma_f32 v[164:165], v[162:163], v[164:165], v[166:167] op_sel_hi:[1,0,1]
	v_pk_mul_f32 v[38:39], v[10:11], 0.5 op_sel_hi:[1,0]
	v_pk_fma_f32 v[10:11], v[10:11], 0.5, v[164:165] op_sel:[0,0,1] op_sel_hi:[1,0,0] neg_lo:[0,0,1] neg_hi:[0,0,1]
	v_pk_add_f32 v[38:39], v[38:39], v[164:165] op_sel:[1,0] op_sel_hi:[0,1]
	v_xor_b32_e32 v166, 0x80000000, v39
	v_mov_b32_e32 v167, v38
	v_pk_mul_f32 v[166:167], v[0:1], v[166:167] op_sel:[1,0]
	v_xor_b32_e32 v165, 0x80000000, v10
	v_pk_fma_f32 v[0:1], v[0:1], v[38:39], v[166:167] op_sel_hi:[0,1,1]
	v_mov_b32_e32 v38, v3
	v_mov_b32_e32 v164, v11
	v_pk_mul_f32 v[10:11], v[38:39], v[10:11] op_sel_hi:[0,1]
	v_pk_fma_f32 v[2:3], v[2:3], v[164:165], v[10:11] op_sel_hi:[0,1,1]
	v_mov_b32_e32 v163, v22
	v_pk_add_f32 v[10:11], v[0:1], v[2:3] neg_lo:[0,1] neg_hi:[0,1]
	v_pk_add_f32 v[0:1], v[0:1], v[2:3]
	v_pk_mul_f32 v[2:3], v[162:163], 0.5 op_sel_hi:[1,0]
	s_nop 0
	v_xor_b32_e32 v22, 0x80000000, v3
	v_mov_b32_e32 v23, v2
	v_pk_mul_f32 v[22:23], v[22:23], v[0:1] op_sel:[0,1]
	s_nop 0
	v_pk_fma_f32 v[2:3], v[2:3], v[10:11], v[22:23] op_sel_hi:[1,0,1]
	v_mov_b32_e32 v10, v0
	v_pk_fma_f32 v[0:1], v[0:1], 0.5, v[2:3] op_sel:[0,0,1] op_sel_hi:[1,0,0] neg_lo:[0,0,1] neg_hi:[0,0,1]
	v_pk_fma_f32 v[22:23], v[10:11], 0.5, v[2:3] op_sel:[0,0,1] op_sel_hi:[1,0,0]
	s_nop 0
	v_mov_b32_e32 v1, v23
	ds_write_b64 v8, v[0:1] offset:8192
	v_pk_fma_f32 v[0:1], v[10:11], 0.5, v[2:3] op_sel_hi:[1,0,0] neg_lo:[1,0,0] neg_hi:[1,0,0]
	s_nop 0
	v_mov_b32_e32 v23, v1
	ds_write_b64 v51, v[22:23]
; __device__ __forceinline__ void pointwise_data(LAS f32x2* X, const f32x4* Hs, int tid) {
;     ...
;     for (int s = tid; s < 8192; s += NTHR) {
;         const f32x4 hh = Hs[s];
;         if (s == 0) {
;             const f32x2 A = X[0]; const float Y0 = (A.x + A.y) * hh.x, YM = (A.x - A.y) * hh.y; X[0] = (f32x2){0.5f * (Y0 + YM), 0.5f * (Y0 - YM)};
;             const f32x2 Cm = X[1]; const f32x2 Y = cmul((f32x2){Cm.x, -Cm.y}, (f32x2){hh.z, hh.w}); X[1] = (f32x2){Y.x, -Y.y};
;         } else {
;             const int i1 = 2 * s, i2 = i1 ^ ((1 << (31 - __clz(i1))) - 1); const int p = (int)(__brev((unsigned)i1) >> 18);
;             const f32x2 A = X[i1], B = X[i2];
;             const f32x2 E = {0.5f * (A.x + B.x), 0.5f * (A.y - B.y)}; const f32x2 Dm = {A.x - B.x, A.y + B.y}; const f32x2 O = {0.5f * Dm.y, -0.5f * Dm.x};
;             const float rev = (float)p * (1.f / 32768.f); const float c = __builtin_amdgcn_cosf(rev), sn = __builtin_amdgcn_sinf(rev);
;             const f32x2 WO = cmul((f32x2){c, -sn}, O);
;             const f32x2 Xk = E + WO; const f32x2 Xk2 = {E.x - WO.x, -(E.y - WO.y)};
;             const f32x2 Yk = cmul(Xk, (f32x2){hh.x, hh.y}), Yk2 = cmul(Xk2, (f32x2){hh.z, hh.w});
;             const f32x2 Ye = {0.5f * (Yk.x + Yk2.x), 0.5f * (Yk.y - Yk2.y)}; const f32x2 Dd = {Yk.x - Yk2.x, Yk.y + Yk2.y};
;             const f32x2 Yo = cmul((f32x2){0.5f * c, 0.5f * sn}, Dd);
;             X[i1] = (f32x2){Ye.x - Yo.y, Ye.y + Yo.x}; X[i2] = (f32x2){Ye.x + Yo.y, Yo.x - Ye.y};
.LBB0_117:
	s_andn2_saveexec_b64 s[74:75], s[74:75]
	s_cbranch_execz .LBB0_119
	ds_read_b128 v[162:165], v173
	s_waitcnt lgkmcnt(0)
	v_add_f32_e32 v10, v162, v163
	v_sub_f32_e32 v22, v162, v163
	v_mul_f32_e32 v23, v0, v10
	v_mul_f32_e32 v1, v1, v22
	v_add_f32_e32 v22, v23, v1
	v_fma_f32 v23, v0, v10, -v1
	v_pk_mul_f32 v[0:1], v[22:23], 0.5 op_sel_hi:[1,0]
	v_mov_b32_e32 v22, v3
	v_xor_b32_e32 v11, 0x80000000, v165
	v_mov_b32_e32 v10, v164
	v_pk_mul_f32 v[22:23], v[22:23], v[164:165] op_sel:[0,1] op_sel_hi:[0,0]
	v_pk_fma_f32 v[2:3], v[2:3], v[10:11], v[22:23] op_sel_hi:[0,1,1]
	v_xor_b32_e32 v3, 0x80000000, v3
	ds_write_b128 v173, v[0:3]
.LBB0_119:
	s_or_b64 exec, exec, s[74:75]
	v_add_u32_e32 v5, 0x200, v5
	s_nop 0
	s_waitcnt vmcnt(3)
	v_mov_b32_e32 v0, v236
	v_mov_b32_e32 v1, v237
	v_mov_b32_e32 v2, v238
	v_mov_b32_e32 v3, v239
	v_add_co_u32_e32 v244, vcc, 0x6000, v6
	s_nop 1
	v_addc_co_u32_e32 v245, vcc, 0, v7, vcc
	global_load_dwordx4 v[236:239], v[244:245], off
	v_cmp_ne_u32_e32 vcc, 0, v5
	s_and_saveexec_b64 s[0:1], vcc
	s_xor_b64 s[74:75], exec, s[0:1]
	s_cbranch_execz .LBB0_121
	v_add_u32_e32 v38, 0xfffffc00, v9
	v_ffbh_u32_e32 v10, v38
	v_lshrrev_b32_e64 v10, v10, s62
	v_add_u32_e32 v10, -1, v10
	v_xor_b32_e32 v22, v10, v38
	v_lshl_add_u32 v51, v22, 3, 0
	v_bfrev_b32_e32 v38, v38
	ds_read_b64 v[10:11], v8 offset:16384
	ds_read_b64 v[22:23], v51
	v_lshrrev_b32_e32 v38, 18, v38
	v_cvt_f32_u32_e32 v53, v38
	s_waitcnt lgkmcnt(0)
	v_pk_add_f32 v[38:39], v[10:11], v[22:23] neg_lo:[0,1] neg_hi:[0,1]
	v_pk_add_f32 v[10:11], v[10:11], v[22:23]
	v_mul_f32_e32 v23, 0x38000000, v53
	v_cos_f32_e32 v162, v23
	v_sin_f32_e32 v22, v23
	v_mul_f32_e32 v166, -0.5, v38
	v_mul_f32_e32 v164, 0.5, v11
	v_mov_b32_e32 v23, v162
	v_xor_b32_e32 v163, 0x80000000, v22
	v_pk_mul_f32 v[166:167], v[22:23], v[166:167] op_sel_hi:[1,0]
	v_pk_mov_b32 v[10:11], v[38:39], v[10:11] op_sel:[1,0]
	v_pk_fma_f32 v[164:165], v[162:163], v[164:165], v[166:167] op_sel_hi:[1,0,1]
	v_pk_mul_f32 v[38:39], v[10:11], 0.5 op_sel_hi:[1,0]
	v_pk_fma_f32 v[10:11], v[10:11], 0.5, v[164:165] op_sel:[0,0,1] op_sel_hi:[1,0,0] neg_lo:[0,0,1] neg_hi:[0,0,1]
	v_pk_add_f32 v[38:39], v[38:39], v[164:165] op_sel:[1,0] op_sel_hi:[0,1]
	v_xor_b32_e32 v166, 0x80000000, v39
	v_mov_b32_e32 v167, v38
	v_pk_mul_f32 v[166:167], v[0:1], v[166:167] op_sel:[1,0]
	v_xor_b32_e32 v165, 0x80000000, v10
	v_pk_fma_f32 v[0:1], v[0:1], v[38:39], v[166:167] op_sel_hi:[0,1,1]
	v_mov_b32_e32 v38, v3
	v_mov_b32_e32 v164, v11
	v_pk_mul_f32 v[10:11], v[38:39], v[10:11] op_sel_hi:[0,1]
	v_pk_fma_f32 v[2:3], v[2:3], v[164:165], v[10:11] op_sel_hi:[0,1,1]
	v_mov_b32_e32 v163, v22
	v_pk_add_f32 v[10:11], v[0:1], v[2:3] neg_lo:[0,1] neg_hi:[0,1]
	v_pk_add_f32 v[0:1], v[0:1], v[2:3]
	v_pk_mul_f32 v[2:3], v[162:163], 0.5 op_sel_hi:[1,0]
	s_nop 0
	v_xor_b32_e32 v22, 0x80000000, v3
	v_mov_b32_e32 v23, v2
	v_pk_mul_f32 v[22:23], v[22:23], v[0:1] op_sel:[0,1]
	s_nop 0
	v_pk_fma_f32 v[2:3], v[2:3], v[10:11], v[22:23] op_sel_hi:[1,0,1]
	v_mov_b32_e32 v10, v0
	v_pk_fma_f32 v[0:1], v[0:1], 0.5, v[2:3] op_sel:[0,0,1] op_sel_hi:[1,0,0] neg_lo:[0,0,1] neg_hi:[0,0,1]
	v_pk_fma_f32 v[22:23], v[10:11], 0.5, v[2:3] op_sel:[0,0,1] op_sel_hi:[1,0,0]
	s_nop 0
	v_mov_b32_e32 v1, v23
	ds_write_b64 v8, v[0:1] offset:16384
	v_pk_fma_f32 v[0:1], v[10:11], 0.5, v[2:3] op_sel_hi:[1,0,0] neg_lo:[1,0,0] neg_hi:[1,0,0]
	s_nop 0
	v_mov_b32_e32 v23, v1
	ds_write_b64 v51, v[22:23]

; __device__ __forceinline__ void pointwise_data(LAS f32x2* X, const f32x4* Hs, int tid) {
;     ...
;     for (int s = tid; s < 8192; s += NTHR) {
;         const f32x4 hh = Hs[s];
;         if (s == 0) {
;             const f32x2 A = X[0]; const float Y0 = (A.x + A.y) * hh.x, YM = (A.x - A.y) * hh.y; X[0] = (f32x2){0.5f * (Y0 + YM), 0.5f * (Y0 - YM)};
;             const f32x2 Cm = X[1]; const f32x2 Y = cmul((f32x2){Cm.x, -Cm.y}, (f32x2){hh.z, hh.w}); X[1] = (f32x2){Y.x, -Y.y};
;         } else {
;             const int i1 = 2 * s, i2 = i1 ^ ((1 << (31 - __clz(i1))) - 1); const int p = (int)(__brev((unsigned)i1) >> 18);
;             const f32x2 A = X[i1], B = X[i2];
;             const f32x2 E = {0.5f * (A.x + B.x), 0.5f * (A.y - B.y)}; const f32x2 Dm = {A.x - B.x, A.y + B.y}; const f32x2 O = {0.5f * Dm.y, -0.5f * Dm.x};
;             const float rev = (float)p * (1.f / 32768.f); const float c = __builtin_amdgcn_cosf(rev), sn = __builtin_amdgcn_sinf(rev);
;             const f32x2 WO = cmul((f32x2){c, -sn}, O);
;             const f32x2 Xk = E + WO; const f32x2 Xk2 = {E.x - WO.x, -(E.y - WO.y)};
;             const f32x2 Yk = cmul(Xk, (f32x2){hh.x, hh.y}), Yk2 = cmul(Xk2, (f32x2){hh.z, hh.w});
;             const f32x2 Ye = {0.5f * (Yk.x + Yk2.x), 0.5f * (Yk.y - Yk2.y)}; const f32x2 Dd = {Yk.x - Yk2.x, Yk.y + Yk2.y};
;             const f32x2 Yo = cmul((f32x2){0.5f * c, 0.5f * sn}, Dd);
;             X[i1] = (f32x2){Ye.x - Yo.y, Ye.y + Yo.x}; X[i2] = (f32x2){Ye.x + Yo.y, Yo.x - Ye.y};
;         }
;     }
;     __syncthreads();
.LBB0_123:
	s_or_b64 exec, exec, s[74:75]
	s_waitcnt vmcnt(3)
	v_mov_b32_e32 v0, v240
	v_mov_b32_e32 v1, v241
	v_mov_b32_e32 v2, v242
	v_mov_b32_e32 v3, v243
	v_add_co_u32_e32 v244, vcc, 0x8000, v6
	s_nop 1
	v_addc_co_u32_e32 v245, vcc, 0, v7, vcc
	global_load_dwordx4 v[240:243], v[244:245], off
	v_cmp_ne_u32_e32 vcc, s83, v5
	s_and_saveexec_b64 s[0:1], vcc
	s_xor_b64 s[74:75], exec, s[0:1]
	s_cbranch_execz .LBB0_125
	v_ffbh_u32_e32 v5, v9
	v_lshrrev_b32_e64 v5, v5, s62
	v_add_u32_e32 v5, -1, v5
	v_xor_b32_e32 v5, v5, v9
	v_lshl_add_u32 v5, v5, 3, 0
	v_bfrev_b32_e32 v38, v9
	ds_read_b64 v[10:11], v8 offset:24576
	ds_read_b64 v[22:23], v5
	v_lshrrev_b32_e32 v38, 18, v38
	v_cvt_f32_u32_e32 v51, v38
	s_waitcnt lgkmcnt(0)
	v_pk_add_f32 v[38:39], v[10:11], v[22:23] neg_lo:[0,1] neg_hi:[0,1]
	v_pk_add_f32 v[10:11], v[10:11], v[22:23]
	v_mul_f32_e32 v23, 0x38000000, v51
	v_cos_f32_e32 v162, v23
	v_sin_f32_e32 v22, v23
	v_mul_f32_e32 v166, -0.5, v38
	v_mul_f32_e32 v164, 0.5, v11
	v_mov_b32_e32 v23, v162
	v_xor_b32_e32 v163, 0x80000000, v22
	v_pk_mul_f32 v[166:167], v[22:23], v[166:167] op_sel_hi:[1,0]
	v_pk_mov_b32 v[10:11], v[38:39], v[10:11] op_sel:[1,0]
	v_pk_fma_f32 v[164:165], v[162:163], v[164:165], v[166:167] op_sel_hi:[1,0,1]
	v_pk_mul_f32 v[38:39], v[10:11], 0.5 op_sel_hi:[1,0]
	v_pk_fma_f32 v[10:11], v[10:11], 0.5, v[164:165] op_sel:[0,0,1] op_sel_hi:[1,0,0] neg_lo:[0,0,1] neg_hi:[0,0,1]
	v_pk_add_f32 v[38:39], v[38:39], v[164:165] op_sel:[1,0] op_sel_hi:[0,1]
	v_xor_b32_e32 v166, 0x80000000, v39
	v_mov_b32_e32 v167, v38
	v_pk_mul_f32 v[166:167], v[0:1], v[166:167] op_sel:[1,0]
	v_xor_b32_e32 v165, 0x80000000, v10
	v_pk_fma_f32 v[0:1], v[0:1], v[38:39], v[166:167] op_sel_hi:[0,1,1]
	v_mov_b32_e32 v38, v3
	v_mov_b32_e32 v164, v11
	v_pk_mul_f32 v[10:11], v[38:39], v[10:11] op_sel_hi:[0,1]
	v_pk_fma_f32 v[2:3], v[2:3], v[164:165], v[10:11] op_sel_hi:[0,1,1]
	v_mov_b32_e32 v163, v22
	v_pk_add_f32 v[10:11], v[0:1], v[2:3] neg_lo:[0,1] neg_hi:[0,1]
	v_pk_add_f32 v[0:1], v[0:1], v[2:3]
	v_pk_mul_f32 v[2:3], v[162:163], 0.5 op_sel_hi:[1,0]
	s_nop 0
	v_xor_b32_e32 v22, 0x80000000, v3
	v_mov_b32_e32 v23, v2
	v_pk_mul_f32 v[22:23], v[22:23], v[0:1] op_sel:[0,1]
	s_nop 0
	v_pk_fma_f32 v[2:3], v[2:3], v[10:11], v[22:23] op_sel_hi:[1,0,1]
	v_mov_b32_e32 v10, v0
	v_pk_fma_f32 v[0:1], v[0:1], 0.5, v[2:3] op_sel:[0,0,1] op_sel_hi:[1,0,0] neg_lo:[0,0,1] neg_hi:[0,0,1]
	v_pk_fma_f32 v[22:23], v[10:11], 0.5, v[2:3] op_sel:[0,0,1] op_sel_hi:[1,0,0]
	s_nop 0
	v_mov_b32_e32 v1, v23
	ds_write_b64 v8, v[0:1] offset:24576
	v_pk_fma_f32 v[0:1], v[10:11], 0.5, v[2:3] op_sel_hi:[1,0,0] neg_lo:[1,0,0] neg_hi:[1,0,0]
	s_nop 0
	v_mov_b32_e32 v23, v1
	ds_write_b64 v5, v[22:23]
.LBB0_125:
	s_andn2_saveexec_b64 s[74:75], s[74:75]
	s_cbranch_execz .LBB0_110
	ds_read_b128 v[162:165], v173
	s_waitcnt lgkmcnt(0)
	v_add_f32_e32 v5, v162, v163
	v_sub_f32_e32 v10, v162, v163
	v_mul_f32_e32 v22, v0, v5
	v_mul_f32_e32 v1, v1, v10
	v_add_f32_e32 v22, v22, v1
	v_fma_f32 v23, v0, v5, -v1
	v_pk_mul_f32 v[0:1], v[22:23], 0.5 op_sel_hi:[1,0]
	v_mov_b32_e32 v22, v3
	v_xor_b32_e32 v11, 0x80000000, v165
	v_mov_b32_e32 v10, v164
	v_pk_mul_f32 v[22:23], v[22:23], v[164:165] op_sel:[0,1] op_sel_hi:[0,0]
	v_pk_fma_f32 v[2:3], v[2:3], v[10:11], v[22:23] op_sel_hi:[0,1,1]
	v_xor_b32_e32 v3, 0x80000000, v3
	ds_write_b128 v173, v[0:3]
	s_branch .LBB0_110
.LBB0_127:
	s_or_b64 exec, exec, s[46:47]
	v_mov_b32_e32 v6, 0
	s_mov_b64 s[78:79], 0
	s_waitcnt vmcnt(0) lgkmcnt(0)
	s_barrier
	s_branch .LBB0_130

; #define LAS __attribute__((address_space(3)))
; __device__ __forceinline__ void pointwise_data(LAS f32x2* X, const f32x4* Hs, int tid) {
; #pragma unroll 4
;     for (int s = tid; s < 8192; s += NTHR) {
;         const f32x4 hh = Hs[s];
.LBB0_171:
	s_or_b64 exec, exec, s[66:67]
	v_readlane_b32 s0, v255, 29
	v_readlane_b32 s1, v255, 30
	s_and_b64 exec, exec, s[0:1]
	s_cbranch_execz .LBB0_190
	v_readlane_b32 s0, v255, 8
	v_ashrrev_i32_e32 v5, 31, v4
	v_readlane_b32 s1, v255, 9
	v_lshl_add_u32 v8, v4, 4, 0
	v_lshl_add_u32 v9, v4, 1, v200
	v_lshl_add_u64 v[6:7], v[4:5], 4, s[0:1]
	s_mov_b64 s[66:67], 0
	v_add_co_u32_e32 v162, vcc, 0xffffa000, v6
	s_nop 1
	v_addc_co_u32_e32 v163, vcc, -1, v7, vcc
	global_load_dwordx4 v[24:27], v[162:163], off
	v_add_co_u32_e32 v162, vcc, 0xffffc000, v6
	s_nop 1
	v_addc_co_u32_e32 v163, vcc, -1, v7, vcc
	global_load_dwordx4 v[28:31], v[162:163], off
	v_add_co_u32_e32 v162, vcc, 0xffffe000, v6
	s_nop 1
	v_addc_co_u32_e32 v163, vcc, -1, v7, vcc
	global_load_dwordx4 v[32:35], v[162:163], off
	global_load_dwordx4 v[36:39], v[6:7], off
	s_branch .LBB0_174

; __device__ __forceinline__ void pointwise_data(LAS f32x2* X, const f32x4* Hs, int tid) {
;     ...
;     for (int s = tid; s < 8192; s += NTHR) {
;         const f32x4 hh = Hs[s];
;         if (s == 0) {
;             const f32x2 A = X[0]; const float Y0 = (A.x + A.y) * hh.x, YM = (A.x - A.y) * hh.y; X[0] = (f32x2){0.5f * (Y0 + YM), 0.5f * (Y0 - YM)};
;             const f32x2 Cm = X[1]; const f32x2 Y = cmul((f32x2){Cm.x, -Cm.y}, (f32x2){hh.z, hh.w}); X[1] = (f32x2){Y.x, -Y.y};
;         } else {
;             const int i1 = 2 * s, i2 = i1 ^ ((1 << (31 - __clz(i1))) - 1); const int p = (int)(__brev((unsigned)i1) >> 18);
;             const f32x2 A = X[i1], B = X[i2];
;             const f32x2 E = {0.5f * (A.x + B.x), 0.5f * (A.y - B.y)}; const f32x2 Dm = {A.x - B.x, A.y + B.y}; const f32x2 O = {0.5f * Dm.y, -0.5f * Dm.x};
;             const float rev = (float)p * (1.f / 32768.f); const float c = __builtin_amdgcn_cosf(rev), sn = __builtin_amdgcn_sinf(rev);
;             const f32x2 WO = cmul((f32x2){c, -sn}, O);
;             const f32x2 Xk = E + WO; const f32x2 Xk2 = {E.x - WO.x, -(E.y - WO.y)};
;             const f32x2 Yk = cmul(Xk, (f32x2){hh.x, hh.y}), Yk2 = cmul(Xk2, (f32x2){hh.z, hh.w});
;             const f32x2 Ye = {0.5f * (Yk.x + Yk2.x), 0.5f * (Yk.y - Yk2.y)}; const f32x2 Dd = {Yk.x - Yk2.x, Yk.y + Yk2.y};
;             const f32x2 Yo = cmul((f32x2){0.5f * c, 0.5f * sn}, Dd);
;             X[i1] = (f32x2){Ye.x - Yo.y, Ye.y + Yo.x}; X[i2] = (f32x2){Ye.x + Yo.y, Yo.x - Ye.y};
.LBB0_174:
	s_nop 1
	s_waitcnt vmcnt(3)
	v_mov_b32_e32 v0, v24
	v_mov_b32_e32 v1, v25
	v_mov_b32_e32 v2, v26
	v_mov_b32_e32 v3, v27
	v_add_co_u32_e32 v162, vcc, 0x2000, v6
	s_nop 1
	v_addc_co_u32_e32 v163, vcc, 0, v7, vcc
	global_load_dwordx4 v[24:27], v[162:163], off
	v_cmp_ne_u32_e32 vcc, 0, v4
	s_and_saveexec_b64 s[0:1], vcc
	s_xor_b64 s[74:75], exec, s[0:1]
	s_cbranch_execz .LBB0_176
	v_add_u32_e32 v5, 0xfffff400, v9
	v_ffbh_u32_e32 v10, v5
	v_lshrrev_b32_e64 v10, v10, s62
	v_add_u32_e32 v10, -1, v10
	v_xor_b32_e32 v12, v10, v5
	v_bfrev_b32_e32 v5, v5
	v_lshrrev_b32_e32 v5, 18, v5
	v_lshl_add_u32 v22, v12, 3, 0
	v_cvt_f32_u32_e32 v5, v5
	ds_read_b64 v[10:11], v8
	ds_read_b64 v[12:13], v22
	v_mul_f32_e32 v5, 0x38000000, v5
	v_cos_f32_e32 v16, v5
	s_waitcnt lgkmcnt(0)
	v_pk_add_f32 v[14:15], v[10:11], v[12:13] neg_lo:[0,1] neg_hi:[0,1]
	v_pk_add_f32 v[10:11], v[10:11], v[12:13]
	v_sin_f32_e32 v12, v5
	v_mul_f32_e32 v20, -0.5, v14
	v_mov_b32_e32 v13, v16
	v_mul_f32_e32 v18, 0.5, v11
	v_xor_b32_e32 v17, 0x80000000, v12
	v_pk_mul_f32 v[20:21], v[12:13], v[20:21] op_sel_hi:[1,0]
	v_pk_mov_b32 v[10:11], v[14:15], v[10:11] op_sel:[1,0]
	v_pk_fma_f32 v[18:19], v[16:17], v[18:19], v[20:21] op_sel_hi:[1,0,1]
	v_pk_mul_f32 v[14:15], v[10:11], 0.5 op_sel_hi:[1,0]
	v_pk_fma_f32 v[10:11], v[10:11], 0.5, v[18:19] op_sel:[0,0,1] op_sel_hi:[1,0,0] neg_lo:[0,0,1] neg_hi:[0,0,1]
	v_pk_add_f32 v[14:15], v[14:15], v[18:19] op_sel:[1,0] op_sel_hi:[0,1]
	v_xor_b32_e32 v20, 0x80000000, v15
	v_mov_b32_e32 v21, v14
	v_pk_mul_f32 v[20:21], v[0:1], v[20:21] op_sel:[1,0]
	v_xor_b32_e32 v19, 0x80000000, v10
	v_pk_fma_f32 v[0:1], v[0:1], v[14:15], v[20:21] op_sel_hi:[0,1,1]
	v_mov_b32_e32 v14, v3
	v_mov_b32_e32 v18, v11
	v_pk_mul_f32 v[10:11], v[14:15], v[10:11] op_sel_hi:[0,1]
	v_pk_fma_f32 v[2:3], v[2:3], v[18:19], v[10:11] op_sel_hi:[0,1,1]
	v_mov_b32_e32 v17, v12
	v_pk_add_f32 v[10:11], v[0:1], v[2:3] neg_lo:[0,1] neg_hi:[0,1]
	v_pk_add_f32 v[0:1], v[0:1], v[2:3]
	v_pk_mul_f32 v[2:3], v[16:17], 0.5 op_sel_hi:[1,0]
	s_nop 0
	v_xor_b32_e32 v12, 0x80000000, v3
	v_mov_b32_e32 v13, v2
	v_pk_mul_f32 v[12:13], v[12:13], v[0:1] op_sel:[0,1]
	s_nop 0
	v_pk_fma_f32 v[2:3], v[2:3], v[10:11], v[12:13] op_sel_hi:[1,0,1]
	v_mov_b32_e32 v10, v0
	v_pk_fma_f32 v[0:1], v[0:1], 0.5, v[2:3] op_sel:[0,0,1] op_sel_hi:[1,0,0] neg_lo:[0,0,1] neg_hi:[0,0,1]
	v_pk_fma_f32 v[12:13], v[10:11], 0.5, v[2:3] op_sel:[0,0,1] op_sel_hi:[1,0,0]
	s_nop 0
	v_mov_b32_e32 v1, v13
	ds_write_b64 v8, v[0:1]
	v_pk_fma_f32 v[0:1], v[10:11], 0.5, v[2:3] op_sel_hi:[1,0,0] neg_lo:[1,0,0] neg_hi:[1,0,0]
	s_nop 0
	v_mov_b32_e32 v13, v1
	ds_write_b64 v22, v[12:13]
.LBB0_176:
	s_andn2_saveexec_b64 s[74:75], s[74:75]
	s_cbranch_execz .LBB0_178
	ds_read_b128 v[10:13], v173
	s_waitcnt lgkmcnt(0)
	v_add_f32_e32 v5, v10, v11
	v_sub_f32_e32 v10, v10, v11
	v_mul_f32_e32 v14, v0, v5
	v_mul_f32_e32 v1, v1, v10
	v_add_f32_e32 v14, v14, v1
	v_fma_f32 v15, v0, v5, -v1
	v_pk_mul_f32 v[0:1], v[14:15], 0.5 op_sel_hi:[1,0]
	v_mov_b32_e32 v14, v3
	v_xor_b32_e32 v11, 0x80000000, v13
	v_mov_b32_e32 v10, v12
	v_pk_mul_f32 v[12:13], v[14:15], v[12:13] op_sel:[0,1] op_sel_hi:[0,0]
	v_pk_fma_f32 v[2:3], v[2:3], v[10:11], v[12:13] op_sel_hi:[0,1,1]
	v_xor_b32_e32 v3, 0x80000000, v3
	ds_write_b128 v173, v[0:3]
.LBB0_178:
	s_or_b64 exec, exec, s[74:75]
	v_add_u32_e32 v5, 0x200, v4
	s_nop 0
	s_waitcnt vmcnt(3)
	v_mov_b32_e32 v0, v28
	v_mov_b32_e32 v1, v29
	v_mov_b32_e32 v2, v30
	v_mov_b32_e32 v3, v31
	v_add_co_u32_e32 v162, vcc, 0x4000, v6
	s_nop 1
	v_addc_co_u32_e32 v163, vcc, 0, v7, vcc
	global_load_dwordx4 v[28:31], v[162:163], off
	v_cmp_ne_u32_e32 vcc, 0, v5
	s_and_saveexec_b64 s[0:1], vcc
	s_xor_b64 s[74:75], exec, s[0:1]
	s_cbranch_execz .LBB0_180
	v_add_u32_e32 v14, 0xfffff800, v9
	v_ffbh_u32_e32 v10, v14
	v_lshrrev_b32_e64 v10, v10, s62
	v_add_u32_e32 v10, -1, v10
	v_xor_b32_e32 v12, v10, v14
	v_lshl_add_u32 v22, v12, 3, 0
	v_bfrev_b32_e32 v14, v14
	ds_read_b64 v[10:11], v8 offset:8192
	ds_read_b64 v[12:13], v22
	v_lshrrev_b32_e32 v14, 18, v14
	v_cvt_f32_u32_e32 v16, v14
	s_waitcnt lgkmcnt(0)
	v_pk_add_f32 v[14:15], v[10:11], v[12:13] neg_lo:[0,1] neg_hi:[0,1]
	v_pk_add_f32 v[10:11], v[10:11], v[12:13]
	v_mul_f32_e32 v13, 0x38000000, v16
	v_cos_f32_e32 v16, v13
	v_sin_f32_e32 v12, v13
	v_mul_f32_e32 v20, -0.5, v14
	v_mul_f32_e32 v18, 0.5, v11
	v_mov_b32_e32 v13, v16
	v_xor_b32_e32 v17, 0x80000000, v12
	v_pk_mul_f32 v[20:21], v[12:13], v[20:21] op_sel_hi:[1,0]
	v_pk_mov_b32 v[10:11], v[14:15], v[10:11] op_sel:[1,0]
	v_pk_fma_f32 v[18:19], v[16:17], v[18:19], v[20:21] op_sel_hi:[1,0,1]
	v_pk_mul_f32 v[14:15], v[10:11], 0.5 op_sel_hi:[1,0]
	v_pk_fma_f32 v[10:11], v[10:11], 0.5, v[18:19] op_sel:[0,0,1] op_sel_hi:[1,0,0] neg_lo:[0,0,1] neg_hi:[0,0,1]
	v_pk_add_f32 v[14:15], v[14:15], v[18:19] op_sel:[1,0] op_sel_hi:[0,1]
	v_xor_b32_e32 v20, 0x80000000, v15
	v_mov_b32_e32 v21, v14
	v_pk_mul_f32 v[20:21], v[0:1], v[20:21] op_sel:[1,0]
	v_xor_b32_e32 v19, 0x80000000, v10
	v_pk_fma_f32 v[0:1], v[0:1], v[14:15], v[20:21] op_sel_hi:[0,1,1]
	v_mov_b32_e32 v14, v3
	v_mov_b32_e32 v18, v11
	v_pk_mul_f32 v[10:11], v[14:15], v[10:11] op_sel_hi:[0,1]
	v_pk_fma_f32 v[2:3], v[2:3], v[18:19], v[10:11] op_sel_hi:[0,1,1]
	v_mov_b32_e32 v17, v12
	v_pk_add_f32 v[10:11], v[0:1], v[2:3] neg_lo:[0,1] neg_hi:[0,1]
	v_pk_add_f32 v[0:1], v[0:1], v[2:3]
	v_pk_mul_f32 v[2:3], v[16:17], 0.5 op_sel_hi:[1,0]
	s_nop 0
	v_xor_b32_e32 v12, 0x80000000, v3
	v_mov_b32_e32 v13, v2
	v_pk_mul_f32 v[12:13], v[12:13], v[0:1] op_sel:[0,1]
	s_nop 0
	v_pk_fma_f32 v[2:3], v[2:3], v[10:11], v[12:13] op_sel_hi:[1,0,1]
	v_mov_b32_e32 v10, v0
	v_pk_fma_f32 v[0:1], v[0:1], 0.5, v[2:3] op_sel:[0,0,1] op_sel_hi:[1,0,0] neg_lo:[0,0,1] neg_hi:[0,0,1]
	v_pk_fma_f32 v[12:13], v[10:11], 0.5, v[2:3] op_sel:[0,0,1] op_sel_hi:[1,0,0]
	s_nop 0
	v_mov_b32_e32 v1, v13
	ds_write_b64 v8, v[0:1] offset:8192
	v_pk_fma_f32 v[0:1], v[10:11], 0.5, v[2:3] op_sel_hi:[1,0,0] neg_lo:[1,0,0] neg_hi:[1,0,0]
	s_nop 0
	v_mov_b32_e32 v13, v1
	ds_write_b64 v22, v[12:13]
; #define LAS __attribute__((address_space(3)))
; __device__ __forceinline__ void pointwise_data(LAS f32x2* X, const f32x4* Hs, int tid) {
; #pragma unroll 4
;     for (int s = tid; s < 8192; s += NTHR) {
;         const f32x4 hh = Hs[s];
;         if (s == 0) {
;             const f32x2 A = X[0]; const float Y0 = (A.x + A.y) * hh.x, YM = (A.x - A.y) * hh.y; X[0] = (f32x2){0.5f * (Y0 + YM), 0.5f * (Y0 - YM)};
;             const f32x2 Cm = X[1]; const f32x2 Y = cmul((f32x2){Cm.x, -Cm.y}, (f32x2){hh.z, hh.w}); X[1] = (f32x2){Y.x, -Y.y};
;         } else {
;             const int i1 = 2 * s, i2 = i1 ^ ((1 << (31 - __clz(i1))) - 1); const int p = (int)(__brev((unsigned)i1) >> 18);
;             const f32x2 A = X[i1], B = X[i2];
;             const f32x2 E = {0.5f * (A.x + B.x), 0.5f * (A.y - B.y)}; const f32x2 Dm = {A.x - B.x, A.y + B.y}; const f32x2 O = {0.5f * Dm.y, -0.5f * Dm.x};
;             const float rev = (float)p * (1.f / 32768.f); const float c = __builtin_amdgcn_cosf(rev), sn = __builtin_amdgcn_sinf(rev);
;             const f32x2 WO = cmul((f32x2){c, -sn}, O);
;             const f32x2 Xk = E + WO; const f32x2 Xk2 = {E.x - WO.x, -(E.y - WO.y)};
;             const f32x2 Yk = cmul(Xk, (f32x2){hh.x, hh.y}), Yk2 = cmul(Xk2, (f32x2){hh.z, hh.w});
;             const f32x2 Ye = {0.5f * (Yk.x + Yk2.x), 0.5f * (Yk.y - Yk2.y)}; const f32x2 Dd = {Yk.x - Yk2.x, Yk.y + Yk2.y};
;             const f32x2 Yo = cmul((f32x2){0.5f * c, 0.5f * sn}, Dd);
;             X[i1] = (f32x2){Ye.x - Yo.y, Ye.y + Yo.x}; X[i2] = (f32x2){Ye.x + Yo.y, Yo.x - Ye.y};
;         }
;     }
;     __syncthreads();
; }
.LBB0_180:
	s_andn2_saveexec_b64 s[74:75], s[74:75]
	s_cbranch_execz .LBB0_182
	ds_read_b128 v[10:13], v173
	s_waitcnt lgkmcnt(0)
	v_add_f32_e32 v15, v10, v11
	v_sub_f32_e32 v10, v10, v11
	v_mul_f32_e32 v14, v0, v15
	v_mul_f32_e32 v1, v1, v10
	v_add_f32_e32 v14, v14, v1
	v_fma_f32 v15, v0, v15, -v1
	v_pk_mul_f32 v[0:1], v[14:15], 0.5 op_sel_hi:[1,0]
	v_mov_b32_e32 v14, v3
	v_xor_b32_e32 v11, 0x80000000, v13
	v_mov_b32_e32 v10, v12
	v_pk_mul_f32 v[12:13], v[14:15], v[12:13] op_sel:[0,1] op_sel_hi:[0,0]
	v_pk_fma_f32 v[2:3], v[2:3], v[10:11], v[12:13] op_sel_hi:[0,1,1]
	v_xor_b32_e32 v3, 0x80000000, v3
	ds_write_b128 v173, v[0:3]
.LBB0_182:
	s_or_b64 exec, exec, s[74:75]
	v_add_u32_e32 v5, 0x200, v5
	s_nop 0
	s_waitcnt vmcnt(3)
	v_mov_b32_e32 v0, v32
	v_mov_b32_e32 v1, v33
	v_mov_b32_e32 v2, v34
	v_mov_b32_e32 v3, v35
	v_add_co_u32_e32 v162, vcc, 0x6000, v6
	s_nop 1
	v_addc_co_u32_e32 v163, vcc, 0, v7, vcc
	global_load_dwordx4 v[32:35], v[162:163], off
	v_cmp_ne_u32_e32 vcc, 0, v5
	s_and_saveexec_b64 s[0:1], vcc
	s_xor_b64 s[74:75], exec, s[0:1]
	s_cbranch_execz .LBB0_184
	v_add_u32_e32 v14, 0xfffffc00, v9
	v_ffbh_u32_e32 v10, v14
	v_lshrrev_b32_e64 v10, v10, s62
	v_add_u32_e32 v10, -1, v10
	v_xor_b32_e32 v12, v10, v14
	v_lshl_add_u32 v22, v12, 3, 0
	v_bfrev_b32_e32 v14, v14
	ds_read_b64 v[10:11], v8 offset:16384
	ds_read_b64 v[12:13], v22
	v_lshrrev_b32_e32 v14, 18, v14
	v_cvt_f32_u32_e32 v16, v14
	s_waitcnt lgkmcnt(0)
	v_pk_add_f32 v[14:15], v[10:11], v[12:13] neg_lo:[0,1] neg_hi:[0,1]
	v_pk_add_f32 v[10:11], v[10:11], v[12:13]
	v_mul_f32_e32 v13, 0x38000000, v16
	v_cos_f32_e32 v16, v13
	v_sin_f32_e32 v12, v13
	v_mul_f32_e32 v20, -0.5, v14
	v_mul_f32_e32 v18, 0.5, v11
	v_mov_b32_e32 v13, v16
	v_xor_b32_e32 v17, 0x80000000, v12
	v_pk_mul_f32 v[20:21], v[12:13], v[20:21] op_sel_hi:[1,0]
	v_pk_mov_b32 v[10:11], v[14:15], v[10:11] op_sel:[1,0]
	v_pk_fma_f32 v[18:19], v[16:17], v[18:19], v[20:21] op_sel_hi:[1,0,1]
	v_pk_mul_f32 v[14:15], v[10:11], 0.5 op_sel_hi:[1,0]
	v_pk_fma_f32 v[10:11], v[10:11], 0.5, v[18:19] op_sel:[0,0,1] op_sel_hi:[1,0,0] neg_lo:[0,0,1] neg_hi:[0,0,1]
	v_pk_add_f32 v[14:15], v[14:15], v[18:19] op_sel:[1,0] op_sel_hi:[0,1]
	v_xor_b32_e32 v20, 0x80000000, v15
	v_mov_b32_e32 v21, v14
	v_pk_mul_f32 v[20:21], v[0:1], v[20:21] op_sel:[1,0]
	v_xor_b32_e32 v19, 0x80000000, v10
	v_pk_fma_f32 v[0:1], v[0:1], v[14:15], v[20:21] op_sel_hi:[0,1,1]
	v_mov_b32_e32 v14, v3
	v_mov_b32_e32 v18, v11
	v_pk_mul_f32 v[10:11], v[14:15], v[10:11] op_sel_hi:[0,1]
	v_pk_fma_f32 v[2:3], v[2:3], v[18:19], v[10:11] op_sel_hi:[0,1,1]
	v_mov_b32_e32 v17, v12
	v_pk_add_f32 v[10:11], v[0:1], v[2:3] neg_lo:[0,1] neg_hi:[0,1]
	v_pk_add_f32 v[0:1], v[0:1], v[2:3]
	v_pk_mul_f32 v[2:3], v[16:17], 0.5 op_sel_hi:[1,0]
	s_nop 0
	v_xor_b32_e32 v12, 0x80000000, v3
	v_mov_b32_e32 v13, v2
	v_pk_mul_f32 v[12:13], v[12:13], v[0:1] op_sel:[0,1]
	s_nop 0
	v_pk_fma_f32 v[2:3], v[2:3], v[10:11], v[12:13] op_sel_hi:[1,0,1]
	v_mov_b32_e32 v10, v0
	v_pk_fma_f32 v[0:1], v[0:1], 0.5, v[2:3] op_sel:[0,0,1] op_sel_hi:[1,0,0] neg_lo:[0,0,1] neg_hi:[0,0,1]
	v_pk_fma_f32 v[12:13], v[10:11], 0.5, v[2:3] op_sel:[0,0,1] op_sel_hi:[1,0,0]
	s_nop 0
	v_mov_b32_e32 v1, v13
	ds_write_b64 v8, v[0:1] offset:16384
	v_pk_fma_f32 v[0:1], v[10:11], 0.5, v[2:3] op_sel_hi:[1,0,0] neg_lo:[1,0,0] neg_hi:[1,0,0]
	s_nop 0
	v_mov_b32_e32 v13, v1
	ds_write_b64 v22, v[12:13]

; #define LAS __attribute__((address_space(3)))
; __device__ __forceinline__ void pointwise_data(LAS f32x2* X, const f32x4* Hs, int tid) {
; #pragma unroll 4
;     for (int s = tid; s < 8192; s += NTHR) {
;         const f32x4 hh = Hs[s];
;         if (s == 0) {
;             const f32x2 A = X[0]; const float Y0 = (A.x + A.y) * hh.x, YM = (A.x - A.y) * hh.y; X[0] = (f32x2){0.5f * (Y0 + YM), 0.5f * (Y0 - YM)};
;             const f32x2 Cm = X[1]; const f32x2 Y = cmul((f32x2){Cm.x, -Cm.y}, (f32x2){hh.z, hh.w}); X[1] = (f32x2){Y.x, -Y.y};
;         } else {
;             const int i1 = 2 * s, i2 = i1 ^ ((1 << (31 - __clz(i1))) - 1); const int p = (int)(__brev((unsigned)i1) >> 18);
;             const f32x2 A = X[i1], B = X[i2];
;             const f32x2 E = {0.5f * (A.x + B.x), 0.5f * (A.y - B.y)}; const f32x2 Dm = {A.x - B.x, A.y + B.y}; const f32x2 O = {0.5f * Dm.y, -0.5f * Dm.x};
;             const float rev = (float)p * (1.f / 32768.f); const float c = __builtin_amdgcn_cosf(rev), sn = __builtin_amdgcn_sinf(rev);
;             const f32x2 WO = cmul((f32x2){c, -sn}, O);
;             const f32x2 Xk = E + WO; const f32x2 Xk2 = {E.x - WO.x, -(E.y - WO.y)};
;             const f32x2 Yk = cmul(Xk, (f32x2){hh.x, hh.y}), Yk2 = cmul(Xk2, (f32x2){hh.z, hh.w});
;             const f32x2 Ye = {0.5f * (Yk.x + Yk2.x), 0.5f * (Yk.y - Yk2.y)}; const f32x2 Dd = {Yk.x - Yk2.x, Yk.y + Yk2.y};
;             const f32x2 Yo = cmul((f32x2){0.5f * c, 0.5f * sn}, Dd);
;             X[i1] = (f32x2){Ye.x - Yo.y, Ye.y + Yo.x}; X[i2] = (f32x2){Ye.x + Yo.y, Yo.x - Ye.y};
;         }
;     }
;     __syncthreads();
; }
.LBB0_186:
	s_or_b64 exec, exec, s[74:75]
	s_waitcnt vmcnt(3)
	v_mov_b32_e32 v0, v36
	v_mov_b32_e32 v1, v37
	v_mov_b32_e32 v2, v38
	v_mov_b32_e32 v3, v39
	v_add_co_u32_e32 v162, vcc, 0x8000, v6
	s_nop 1
	v_addc_co_u32_e32 v163, vcc, 0, v7, vcc
	global_load_dwordx4 v[36:39], v[162:163], off
	v_cmp_ne_u32_e32 vcc, s83, v5
	s_and_saveexec_b64 s[0:1], vcc
	s_xor_b64 s[74:75], exec, s[0:1]
	s_cbranch_execz .LBB0_188
	v_ffbh_u32_e32 v5, v9
	v_lshrrev_b32_e64 v5, v5, s62
	v_add_u32_e32 v5, -1, v5
	v_xor_b32_e32 v5, v5, v9
	v_lshl_add_u32 v5, v5, 3, 0
	v_bfrev_b32_e32 v14, v9
	ds_read_b64 v[10:11], v8 offset:24576
	ds_read_b64 v[12:13], v5
	v_lshrrev_b32_e32 v14, 18, v14
	v_cvt_f32_u32_e32 v16, v14
	s_waitcnt lgkmcnt(0)
	v_pk_add_f32 v[14:15], v[10:11], v[12:13] neg_lo:[0,1] neg_hi:[0,1]
	v_pk_add_f32 v[10:11], v[10:11], v[12:13]
	v_mul_f32_e32 v13, 0x38000000, v16
	v_cos_f32_e32 v16, v13
	v_sin_f32_e32 v12, v13
	v_mul_f32_e32 v20, -0.5, v14
	v_mul_f32_e32 v18, 0.5, v11
	v_mov_b32_e32 v13, v16
	v_xor_b32_e32 v17, 0x80000000, v12
	v_pk_mul_f32 v[20:21], v[12:13], v[20:21] op_sel_hi:[1,0]
	v_pk_mov_b32 v[10:11], v[14:15], v[10:11] op_sel:[1,0]
	v_pk_fma_f32 v[18:19], v[16:17], v[18:19], v[20:21] op_sel_hi:[1,0,1]
	v_pk_mul_f32 v[14:15], v[10:11], 0.5 op_sel_hi:[1,0]
	v_pk_fma_f32 v[10:11], v[10:11], 0.5, v[18:19] op_sel:[0,0,1] op_sel_hi:[1,0,0] neg_lo:[0,0,1] neg_hi:[0,0,1]
	v_pk_add_f32 v[14:15], v[14:15], v[18:19] op_sel:[1,0] op_sel_hi:[0,1]
	v_xor_b32_e32 v20, 0x80000000, v15
	v_mov_b32_e32 v21, v14
	v_pk_mul_f32 v[20:21], v[0:1], v[20:21] op_sel:[1,0]
	v_xor_b32_e32 v19, 0x80000000, v10
	v_pk_fma_f32 v[0:1], v[0:1], v[14:15], v[20:21] op_sel_hi:[0,1,1]
	v_mov_b32_e32 v14, v3
	v_mov_b32_e32 v18, v11
	v_pk_mul_f32 v[10:11], v[14:15], v[10:11] op_sel_hi:[0,1]
	v_pk_fma_f32 v[2:3], v[2:3], v[18:19], v[10:11] op_sel_hi:[0,1,1]
	v_mov_b32_e32 v17, v12
	v_pk_add_f32 v[10:11], v[0:1], v[2:3] neg_lo:[0,1] neg_hi:[0,1]
	v_pk_add_f32 v[0:1], v[0:1], v[2:3]
	v_pk_mul_f32 v[2:3], v[16:17], 0.5 op_sel_hi:[1,0]
	s_nop 0
	v_xor_b32_e32 v12, 0x80000000, v3
	v_mov_b32_e32 v13, v2
	v_pk_mul_f32 v[12:13], v[12:13], v[0:1] op_sel:[0,1]
	s_nop 0
	v_pk_fma_f32 v[2:3], v[2:3], v[10:11], v[12:13] op_sel_hi:[1,0,1]
	v_mov_b32_e32 v10, v0
	v_pk_fma_f32 v[0:1], v[0:1], 0.5, v[2:3] op_sel:[0,0,1] op_sel_hi:[1,0,0] neg_lo:[0,0,1] neg_hi:[0,0,1]
	v_pk_fma_f32 v[12:13], v[10:11], 0.5, v[2:3] op_sel:[0,0,1] op_sel_hi:[1,0,0]
	s_nop 0
	v_mov_b32_e32 v1, v13
	ds_write_b64 v8, v[0:1] offset:24576
	v_pk_fma_f32 v[0:1], v[10:11], 0.5, v[2:3] op_sel_hi:[1,0,0] neg_lo:[1,0,0] neg_hi:[1,0,0]
	s_nop 0
	v_mov_b32_e32 v13, v1
	ds_write_b64 v5, v[12:13]
.LBB0_188:
	s_andn2_saveexec_b64 s[74:75], s[74:75]
	s_cbranch_execz .LBB0_173
	ds_read_b128 v[10:13], v173
	s_waitcnt lgkmcnt(0)
	v_add_f32_e32 v5, v10, v11
	v_sub_f32_e32 v10, v10, v11
	v_mul_f32_e32 v14, v0, v5
	v_mul_f32_e32 v1, v1, v10
	v_add_f32_e32 v14, v14, v1
	v_fma_f32 v15, v0, v5, -v1
	v_pk_mul_f32 v[0:1], v[14:15], 0.5 op_sel_hi:[1,0]
	v_mov_b32_e32 v14, v3
	v_xor_b32_e32 v11, 0x80000000, v13
	v_mov_b32_e32 v10, v12
	v_pk_mul_f32 v[12:13], v[14:15], v[12:13] op_sel:[0,1] op_sel_hi:[0,0]
	v_pk_fma_f32 v[2:3], v[2:3], v[10:11], v[12:13] op_sel_hi:[0,1,1]
	v_xor_b32_e32 v3, 0x80000000, v3
	ds_write_b128 v173, v[0:3]
	s_branch .LBB0_173

; #define LAS __attribute__((address_space(3)))
; __device__ __forceinline__ void attn_phase(const LArgs& a, LAS unsigned char* lds) {
;     ...
;         for (int j = 0; j < NT; ++j) {
;             const int cur = j & 1;
;             if (j + 1 < NT) ATT_LOAD(j + 1);
;             if (late && j > 0) ATT_PV(vprev, 0);
;             const LAS unsigned char* kb_ = lds + cur * KBUF;
;             f32x16 s[2];
; #pragma unroll
;             for (int kb = 0; kb < 2; ++kb) {
; #pragma unroll
;                 for (int r = 0; r < 16; ++r) s[kb][r] = 0.f;
; #pragma unroll
;                 for (int ks = 0; ks < 4; ++ks) { const bf16x8 kf = *(const LAS bf16x8*)(kb_ + (32 * kb + kappa) * KROW + mp * 128 + ks * 32 + hi * 16);
;                     s[kb] = __builtin_amdgcn_mfma_f32_32x32x16_bf16(kf, qf[ks], s[kb], 0, 0, 0); }
;             }
;             if (!late) ATT_PV_PRE(vcur);
;             float mx = s[0][0];
; #pragma unroll
;             for (int r = 1; r < 16; ++r) mx = fmaxf(mx, s[0][r]);
; #pragma unroll
;             for (int r = 0; r < 16; ++r) mx = fmaxf(mx, s[1][r]);
;             mx = fmaxf(mx, xor32_get(mx, xaddr));
;             const float mnew = fmaxf(mrun, mx);
;             if (__any(mnew > mrun)) {
;                 const float alpha = __builtin_amdgcn_exp2f(mrun - mnew); lrun *= alpha;
; #pragma unroll
;                 for (int d = 0; d < 4; ++d)
; #pragma unroll
;                     for (int r = 0; r < 16; ++r) o[d][r] *= alpha;
;                 mrun = mnew;
;             }
;             float psum = 0.f;
; #pragma unroll
;             for (int kb = 0; kb < 2; ++kb)
; #pragma unroll
;                 for (int r = 0; r < 16; ++r) { const float pv = __builtin_amdgcn_exp2f(s[kb][r] - mrun); s[kb][r] = pv; psum += pv; }
;             lrun += psum;
; #pragma unroll
;             for (int kb = 0; kb < 2; ++kb)
; #pragma unroll
;                 for (int g = 0; g < 2; ++g) {
;                     u32x4 w4; w4.x = pg8::cvt_pk_bf16(s[kb][8 * g + 0], s[kb][8 * g + 1]); w4.y = pg8::cvt_pk_bf16(s[kb][8 * g + 2], s[kb][8 * g + 3]);
;                     w4.z = pg8::cvt_pk_bf16(s[kb][8 * g + 4], s[kb][8 * g + 5]); w4.w = pg8::cvt_pk_bf16(s[kb][8 * g + 6], s[kb][8 * g + 7]);
;                     pw[2 * kb + g] = w4;
;                 }
;             if (!late) ATT_PV(vcur, 1);
;             if (j + 1 < NT) ATT_STORE(cur ^ 1, vnext);
.Lattn_noload:
	s_and_b32 s23, s21, 1
	s_mul_i32 s16, s23, 0x4400
	s_mul_i32 s24, s22, 0x4800
	v_add_u32_e32 v252, s16, v171
	v_add3_u32 v218, s24, v148, v178
	ds_read_b128 v[96:99], v252
	ds_read_b128 v[100:103], v252 offset:32
	ds_read_b128 v[104:107], v252 offset:64
	ds_read_b128 v[108:111], v252 offset:96
	ds_read_b128 v[182:185], v252 offset:8704
	ds_read_b128 v[186:189], v252 offset:8736
	ds_read_b128 v[224:227], v252 offset:8768
	ds_read_b128 v[244:247], v252 offset:8800
	ds_read_b128 v[174:177], v218 offset:34816
	ds_read_b128 v[248:251], v218 offset:39424
	s_waitcnt lgkmcnt(9)
	v_mfma_f32_32x32x16_bf16 v[228:243], v[96:99], v[112:115], v[202:217]
	ds_read_b128 v[96:99], v218 offset:44032
	s_waitcnt lgkmcnt(9)
	v_mfma_f32_32x32x16_bf16 v[228:243], v[100:103], v[116:119], v[228:243]
	ds_read_b128 v[100:103], v218 offset:48640
	s_waitcnt lgkmcnt(9)
	v_mfma_f32_32x32x16_bf16 v[228:243], v[104:107], v[120:123], v[228:243]
	ds_read_b128 v[104:107], v218 offset:34848
	s_waitcnt lgkmcnt(9)
	v_mfma_f32_32x32x16_bf16 v[228:243], v[108:111], v[124:127], v[228:243]
	ds_read_b128 v[108:111], v218 offset:39456
	s_waitcnt lgkmcnt(9)
	v_mfma_f32_32x32x16_bf16 v[64:79], v[182:185], v[112:115], v[202:217]
	ds_read_b128 v[182:185], v218 offset:44064
	s_waitcnt lgkmcnt(9)
	v_mfma_f32_32x32x16_bf16 v[64:79], v[186:189], v[116:119], v[64:79]
	ds_read_b128 v[186:189], v218 offset:48672
	s_waitcnt lgkmcnt(9)
	v_mfma_f32_32x32x16_bf16 v[64:79], v[224:227], v[120:123], v[64:79]
	ds_read_b128 v[224:227], v218 offset:34880
	s_waitcnt lgkmcnt(9)
	v_mfma_f32_32x32x16_bf16 v[64:79], v[244:247], v[124:127], v[64:79]
	ds_read_b128 v[244:247], v218 offset:39488
	s_waitcnt lgkmcnt(9)
	v_mfma_f32_32x32x16_bf16 v[48:63], v[174:177], v[92:95], v[48:63]
	ds_read_b128 v[174:177], v218 offset:44096
	v_exp_f32_e32 v228, v228
	v_exp_f32_e32 v229, v229
	v_exp_f32_e32 v230, v230
	v_exp_f32_e32 v231, v231
	s_waitcnt lgkmcnt(9)
	v_mfma_f32_32x32x16_bf16 v[32:47], v[248:251], v[92:95], v[32:47]
	ds_read_b128 v[248:251], v218 offset:48704
	v_exp_f32_e32 v232, v232
	v_exp_f32_e32 v233, v233
	v_exp_f32_e32 v234, v234
	v_exp_f32_e32 v235, v235
	s_waitcnt lgkmcnt(9)
	v_mfma_f32_32x32x16_bf16 v[16:31], v[96:99], v[92:95], v[16:31]
	ds_read_b128 v[96:99], v218 offset:34912
	v_exp_f32_e32 v236, v236
	v_exp_f32_e32 v237, v237
	v_exp_f32_e32 v238, v238
	v_exp_f32_e32 v239, v239
	s_waitcnt lgkmcnt(9)
	v_mfma_f32_32x32x16_bf16 v[0:15], v[100:103], v[92:95], v[0:15]
	ds_read_b128 v[100:103], v218 offset:39520
	v_exp_f32_e32 v240, v240
	v_exp_f32_e32 v241, v241
	v_exp_f32_e32 v242, v242
	v_exp_f32_e32 v243, v243
	s_waitcnt lgkmcnt(9)
	v_mfma_f32_32x32x16_bf16 v[48:63], v[104:107], v[88:91], v[48:63]
	ds_read_b128 v[104:107], v218 offset:44128
	v_exp_f32_e32 v64, v64
	v_exp_f32_e32 v65, v65
	v_exp_f32_e32 v66, v66
	v_exp_f32_e32 v67, v67
	s_waitcnt lgkmcnt(9)
	v_mfma_f32_32x32x16_bf16 v[32:47], v[108:111], v[88:91], v[32:47]
	ds_read_b128 v[108:111], v218 offset:48736
	v_exp_f32_e32 v68, v68
	v_exp_f32_e32 v69, v69
	v_exp_f32_e32 v70, v70
	v_exp_f32_e32 v71, v71
	s_waitcnt lgkmcnt(9)
	v_mfma_f32_32x32x16_bf16 v[16:31], v[182:185], v[88:91], v[16:31]
	v_exp_f32_e32 v72, v72
	v_exp_f32_e32 v73, v73
	v_exp_f32_e32 v74, v74
	v_exp_f32_e32 v75, v75
	s_waitcnt lgkmcnt(8)
	v_mfma_f32_32x32x16_bf16 v[0:15], v[186:189], v[88:91], v[0:15]
	v_exp_f32_e32 v76, v76
	v_exp_f32_e32 v77, v77
	v_exp_f32_e32 v78, v78
	v_exp_f32_e32 v79, v79
	s_andn2_b64 vcc, exec, s[0:1]
	s_cbranch_vccnz .Lattn_nowrite
	s_xor_b32 s0, s23, 1
	s_mulk_i32 s0, 0x4400
	s_mul_i32 s1, s20, 0x4800
	v_add_u32_e32 v219, s0, v168
	s_waitcnt vmcnt(3)
	ds_write_b128 v219, v[128:131]
	s_waitcnt vmcnt(2)
	ds_write_b128 v219, v[132:135] offset:8704
	v_add_u32_e32 v219, s1, v169
	s_waitcnt vmcnt(1)
	ds_write_b128 v219, v[136:139] offset:34816
	s_waitcnt vmcnt(0)
	ds_write_b128 v219, v[140:143] offset:44032
.Lattn_nowrite:
	s_waitcnt lgkmcnt(7)
	v_mfma_f32_32x32x16_bf16 v[48:63], v[224:227], v[84:87], v[48:63]
	v_add_f32_e32 v190, v228, v229
	v_add_f32_e32 v191, v64, v65
	v_add_f32_e32 v190, v190, v230
	v_add_f32_e32 v191, v191, v66
	v_add_f32_e32 v190, v190, v231
	v_add_f32_e32 v191, v191, v67
	s_waitcnt lgkmcnt(6)
	v_mfma_f32_32x32x16_bf16 v[32:47], v[244:247], v[84:87], v[32:47]
	v_add_f32_e32 v190, v190, v232
	v_add_f32_e32 v191, v191, v68
	v_add_f32_e32 v190, v190, v233
	v_add_f32_e32 v191, v191, v69
	v_add_f32_e32 v190, v190, v234
	v_add_f32_e32 v191, v191, v70
	s_waitcnt lgkmcnt(5)
	v_mfma_f32_32x32x16_bf16 v[16:31], v[174:177], v[84:87], v[16:31]
	v_add_f32_e32 v190, v190, v235
	v_add_f32_e32 v191, v191, v71
	v_add_f32_e32 v190, v190, v236
	v_add_f32_e32 v191, v191, v72
	v_add_f32_e32 v190, v190, v237
	v_add_f32_e32 v191, v191, v73
	s_waitcnt lgkmcnt(4)
	v_mfma_f32_32x32x16_bf16 v[0:15], v[248:251], v[84:87], v[0:15]
	v_add_f32_e32 v190, v190, v238
	v_add_f32_e32 v191, v191, v74
	v_add_f32_e32 v190, v190, v239
	v_add_f32_e32 v191, v191, v75
	v_add_f32_e32 v190, v190, v240
	v_add_f32_e32 v191, v191, v76
	s_waitcnt lgkmcnt(3)
	v_mfma_f32_32x32x16_bf16 v[48:63], v[96:99], v[80:83], v[48:63]
	v_add_f32_e32 v190, v190, v241
	v_add_f32_e32 v191, v191, v77
	v_add_f32_e32 v190, v190, v242
	v_add_f32_e32 v191, v191, v78
	s_waitcnt lgkmcnt(2)
	v_mfma_f32_32x32x16_bf16 v[32:47], v[100:103], v[80:83], v[32:47]
	v_add_f32_e32 v190, v190, v243
	v_add_f32_e32 v191, v191, v79
	v_add_f32_e32 v190, v190, v191
	s_waitcnt lgkmcnt(1)
	v_mfma_f32_32x32x16_bf16 v[16:31], v[104:107], v[80:83], v[16:31]
	v_cvt_pk_bf16_f32 v92, v228, v229
	v_cvt_pk_bf16_f32 v93, v230, v231
	v_cvt_pk_bf16_f32 v94, v232, v233
	v_cvt_pk_bf16_f32 v95, v234, v235
	s_waitcnt lgkmcnt(0)
	v_mfma_f32_32x32x16_bf16 v[0:15], v[108:111], v[80:83], v[0:15]
	v_cvt_pk_bf16_f32 v88, v236, v237
	v_cvt_pk_bf16_f32 v89, v238, v239
	v_cvt_pk_bf16_f32 v90, v240, v241
	v_cvt_pk_bf16_f32 v91, v242, v243
	v_cmp_lt_f32_e32 vcc, 0x43800000, v190
	s_cbranch_vccnz .Lattn_rare
	v_add_f32_e32 v149, v149, v190
	v_cvt_pk_bf16_f32 v84, v64, v65
	v_cvt_pk_bf16_f32 v85, v66, v67
	v_cvt_pk_bf16_f32 v86, v68, v69
	v_cvt_pk_bf16_f32 v87, v70, v71
	v_cvt_pk_bf16_f32 v80, v72, v73
	v_cvt_pk_bf16_f32 v81, v74, v75
	v_cvt_pk_bf16_f32 v82, v76, v77
	v_cvt_pk_bf16_f32 v83, v78, v79
